# XCD-local seams for P3|P4 (spatial gating items re-distributed class-locally) and P10|P11 when the placement census allows; else unchanged barrier
# baseline (speedup 1.0000x reference)
; __device__ __forceinline__ unsigned xb_ld(unsigned* p)              { return __hip_atomic_load(p, __ATOMIC_RELAXED, __HIP_MEMORY_SCOPE_AGENT); }
; __device__ __forceinline__ void xcd_barrier_complete(unsigned* bar, unsigned x, unsigned& nloc, unsigned& nx) {
;     const unsigned G = gridDim.x * gridDim.y * gridDim.z;
;     unsigned sum, cnt, mine, sp = 0u;
;     for (;;) {
;         sum = 0u; cnt = 0u; mine = 0u;
; #pragma unroll
;         for (unsigned j = 0; j < 16; ++j) { const unsigned c = xb_ld(&bar[XB_XCNT(j)]); sum += c; cnt += (c > 0u) ? 1u : 0u; mine = (j == x) ? c : mine; }
;         if (sum == G) break;
;         __builtin_amdgcn_s_sleep(1);
;         if ((++sp & 255u) == 0u) { if (xb_ld(&bar[XB_TMO])) break; if (sp > XB_SPIN_CAP) { atomicAdd(&bar[XB_TMO], 1u); break; } }
;     }
;     nloc = mine > 0u ? mine : 1u; nx = cnt > 0u ? cnt : 1u;
; }
; __device__ __forceinline__ void xcd_barrier(const XcdBarrier& b) {
;     asm volatile("s_waitcnt vmcnt(0)" ::: "memory");
;     __syncthreads();
;     if (threadIdx.x == 0) {
;         unsigned* bar = b.bar;
;         __builtin_amdgcn_s_waitcnt(0);
;         unsigned nloc = b.st[0], nx = b.st[1];
;         if (nloc == 0u) { xcd_barrier_complete(bar, b.x, nloc, nx); b.st[0] = nloc; b.st[1] = nx; }
.LBB0_274:
	s_mov_b64 s[90:91], exec
	s_add_u32 s6, s4, 0x200
	s_addc_u32 s7, s5, 0
	s_mov_b64 exec, 0xffff
	v_mbcnt_lo_u32_b32 v16, -1, 0
	v_lshlrev_b32_e32 v16, 8, v16
	global_load_dword v17, v16, s[6:7] sc1
	s_waitcnt vmcnt(0)
	v_cmp_eq_u32_e32 vcc, 32, v17
	v_cmp_eq_u32_e64 s[36:37], 0, v17
	s_or_b64 s[36:37], s[36:37], vcc
	global_load_dword v17, v16, s[6:7] offset:128 sc1
	s_waitcnt vmcnt(0)
	v_lshrrev_b32_e32 v16, 16, v17
	v_and_b32_e32 v17, 0xffff, v17
	v_mul_lo_u32 v17, v17, v17
	v_lshlrev_b32_e32 v16, 5, v16
	v_cmp_eq_u32_e32 vcc, v16, v17
	s_and_b64 s[36:37], s[36:37], vcc
	s_mov_b64 exec, s[90:91]
	s_cmp_eq_u64 s[36:37], 0xffff
	s_cselect_b32 s98, 1, 0
	s_and_b32 s98, s98, s12
	v_mov_b32_e32 v16, 0x20408
	v_mov_b32_e32 v17, s98
	ds_write_b32 v16, v17
	s_cmp_eq_u32 s97, 0
	s_cselect_b64 vcc, -1, 0
	s_cmp_eq_u32 s97, 1
	v_cndmask_b32_e32 v16, 0, v15, vcc
	s_cselect_b64 vcc, -1, 0
	s_cmp_eq_u32 s97, 2
	v_cndmask_b32_e32 v16, v16, v0, vcc
	s_cselect_b64 vcc, -1, 0
	s_cmp_eq_u32 s97, 3
	v_cndmask_b32_e32 v16, v16, v1, vcc
	s_cselect_b64 vcc, -1, 0
	s_cmp_eq_u32 s97, 4
	v_cndmask_b32_e32 v16, v16, v2, vcc
	s_cselect_b64 vcc, -1, 0
	s_cmp_eq_u32 s97, 5
	v_cndmask_b32_e32 v16, v16, v3, vcc
	s_cselect_b64 vcc, -1, 0
	s_cmp_eq_u32 s97, 6
	v_cndmask_b32_e32 v16, v16, v4, vcc
	s_cselect_b64 vcc, -1, 0
	s_cmp_eq_u32 s97, 7
	v_cndmask_b32_e32 v16, v16, v5, vcc
	s_cselect_b64 vcc, -1, 0
	s_cmp_eq_u32 s97, 8
	v_cndmask_b32_e32 v16, v16, v6, vcc
	s_cselect_b64 vcc, -1, 0
	s_cmp_eq_u32 s97, 9
	v_cndmask_b32_e32 v16, v16, v7, vcc
	s_cselect_b64 vcc, -1, 0
	s_cmp_eq_u32 s97, 10
	v_cndmask_b32_e32 v16, v16, v8, vcc
	s_cselect_b64 vcc, -1, 0
	s_cmp_eq_u32 s97, 11
	v_cndmask_b32_e32 v16, v16, v9, vcc
	s_cselect_b64 vcc, -1, 0
	s_cmp_eq_u32 s97, 12
	v_cndmask_b32_e32 v16, v16, v10, vcc
	s_cselect_b64 vcc, -1, 0
	s_cmp_eq_u32 s97, 13
	v_cndmask_b32_e32 v16, v16, v11, vcc
	s_cselect_b64 vcc, -1, 0
	s_cmp_eq_u32 s97, 14
	v_cndmask_b32_e32 v16, v16, v12, vcc
	s_cselect_b64 vcc, -1, 0
	s_cmp_eq_u32 s97, 15
	v_cndmask_b32_e32 v16, v16, v13, vcc
	s_cselect_b64 vcc, -1, 0
	v_cndmask_b32_e32 v16, v16, v14, vcc
	v_cmp_ne_u32_e32 vcc, 0, v15
	s_add_i32 s4, 0, 0x20400
	s_nop 0
	v_cndmask_b32_e64 v15, 0, 1, vcc
	v_cmp_ne_u32_e32 vcc, 0, v0
	s_nop 1
	v_addc_co_u32_e32 v0, vcc, 0, v15, vcc
	v_cmp_ne_u32_e32 vcc, 0, v1
	s_nop 1
	v_cndmask_b32_e64 v1, 0, 1, vcc
	v_cmp_ne_u32_e32 vcc, 0, v2
	v_max_u32_e32 v2, 1, v16
	s_nop 0
	v_addc_co_u32_e32 v0, vcc, v0, v1, vcc
	v_cmp_ne_u32_e32 vcc, 0, v3
	s_nop 1
	v_cndmask_b32_e64 v1, 0, 1, vcc
	v_cmp_ne_u32_e32 vcc, 0, v4
	s_nop 1
	v_addc_co_u32_e32 v0, vcc, v0, v1, vcc
	v_cmp_ne_u32_e32 vcc, 0, v5
	s_nop 1
	v_cndmask_b32_e64 v1, 0, 1, vcc
	v_cmp_ne_u32_e32 vcc, 0, v6
	s_nop 1
	v_addc_co_u32_e32 v0, vcc, v0, v1, vcc
	v_cmp_ne_u32_e32 vcc, 0, v7
	s_nop 1
	v_cndmask_b32_e64 v1, 0, 1, vcc
	v_cmp_ne_u32_e32 vcc, 0, v8
	s_nop 1
	v_addc_co_u32_e32 v0, vcc, v0, v1, vcc
	v_cmp_ne_u32_e32 vcc, 0, v9
	s_nop 1
	v_cndmask_b32_e64 v1, 0, 1, vcc
	v_cmp_ne_u32_e32 vcc, 0, v10
	s_nop 1
	v_addc_co_u32_e32 v0, vcc, v0, v1, vcc
	v_cmp_ne_u32_e32 vcc, 0, v11
	s_nop 1
	v_cndmask_b32_e64 v1, 0, 1, vcc
	v_cmp_ne_u32_e32 vcc, 0, v12
	s_nop 1
	v_addc_co_u32_e32 v0, vcc, v0, v1, vcc
	v_cmp_ne_u32_e32 vcc, 0, v13
	s_nop 1
	v_cndmask_b32_e64 v1, 0, 1, vcc
	v_cmp_ne_u32_e32 vcc, 0, v14
	s_nop 1
	v_addc_co_u32_e32 v0, vcc, v0, v1, vcc
	v_mov_b32_e32 v1, s4
	s_add_i32 s4, 0, 0x20404
	v_max_u32_e32 v0, 1, v0
	ds_write_b32 v1, v2
	v_mov_b32_e32 v1, s4
	ds_write_b32 v1, v0

; __device__ __forceinline__ unsigned xb_ld(unsigned* p)              { return __hip_atomic_load(p, __ATOMIC_RELAXED, __HIP_MEMORY_SCOPE_AGENT); }
; __device__ __forceinline__ unsigned xb_add(unsigned* p, unsigned v) { return __hip_atomic_fetch_add(p, v, __ATOMIC_RELAXED, __HIP_MEMORY_SCOPE_AGENT); }
; #define XB_SPIN(cond, bar) do { unsigned _sp = 0; while (cond) { __builtin_amdgcn_s_sleep(1); \
;     if ((++_sp & 255u) == 0u) { if (xb_ld(&(bar)[XB_TMO])) break; if (_sp > XB_SPIN_CAP) { atomicAdd(&(bar)[XB_TMO], 1u); break; } } } } while (0)
; __device__ __forceinline__ void xcd_barrier(const XcdBarrier& b) {
;     ...
;         const unsigned old = xb_add(&bar[XB_XSUB(b.x)], 1u);
;         const unsigned gen = old / nloc;
;         if (old + 1u == (gen + 1u) * nloc) {
;             __builtin_amdgcn_fence(__ATOMIC_RELEASE, "agent");
;             asm volatile("s_waitcnt vmcnt(0)" ::: "memory");
;             const unsigned og = xb_add(&bar[XB_TOP], 1u);
;             const unsigned tg = og / nx;
;             if (og + 1u == (tg + 1u) * nx) xb_add(&bar[XB_TOPGEN], 1u);
;             else XB_SPIN(xb_ld(&bar[XB_TOPGEN]) == tg, bar);
;             __builtin_amdgcn_fence(__ATOMIC_ACQUIRE, "agent");
;             xb_add(&bar[XB_XGEN(b.x)], 1u);
.LBB0_1166:
	s_andn2_saveexec_b64 s[6:7], s[6:7]
	s_cbranch_execz .LBB0_1186
	s_mov_b64 s[6:7], exec
	s_waitcnt lgkmcnt(0)
	s_cmp_lg_u32 s98, 0
	s_cbranch_scc1 .LBB0_1183
	buffer_wbl2 sc1
	s_waitcnt lgkmcnt(0)
	s_waitcnt vmcnt(0)
	v_mbcnt_lo_u32_b32 v1, s6, 0
	v_mbcnt_hi_u32_b32 v1, s7, v1
	v_cmp_eq_u32_e32 vcc, 0, v1
	s_and_saveexec_b64 s[8:9], vcc
	s_cbranch_execz .LBB0_1169
	s_bcnt1_i32_b64 s6, s[6:7]
	v_readlane_b32 s12, v249, 1
	v_mov_b32_e32 v2, 0x3583000
	v_mov_b32_e32 v3, s6
	v_readlane_b32 s26, v249, 15
	v_readlane_b32 s27, v249, 16
	v_readlane_b32 s13, v249, 2
	v_readlane_b32 s14, v249, 3
	v_readlane_b32 s15, v249, 4
	v_readlane_b32 s16, v249, 5
	v_readlane_b32 s17, v249, 6
	global_atomic_add v2, v2, v3, s[26:27] offset:1024 sc0
	v_readlane_b32 s18, v249, 7
	v_readlane_b32 s19, v249, 8
	v_readlane_b32 s20, v249, 9
	v_readlane_b32 s21, v249, 10
	v_readlane_b32 s22, v249, 11
	v_readlane_b32 s23, v249, 12
	v_readlane_b32 s24, v249, 13
	v_readlane_b32 s25, v249, 14

; #define LAS __attribute__((address_space(3)))
; DI void sgu_item(int g, int bc, int par, const bf16_t* SGW, const bf16_t* Vg, const float* VST, const float* lng, const float* lnb, const float* sgb, bf16_t* U, LAS unsigned char* lds) {
;     constexpr int RS = 272;
;     const int tid = threadIdx.x, lane = tid & 63, w = __builtin_amdgcn_readfirstlane(tid >> 6), row0 = bc * 128;
;     LAS unsigned char* Wl = lds + par * (192 * RS); LAS unsigned char* Vl = Wl + 128 * RS;
;     const int j = lane & 15, q = lane >> 4, t0 = 16 * w, nks = (t0 + 15) / 32 + 1, t = t0 + j;
;     u32x4 wreg[4];
; #pragma unroll
;     for (int i = 0; i < 4; ++i) { const int c = tid + i * 512, rr = c >> 4, cc = c & 15; wreg[i] = *(const u32x4*)(SGW + (size_t)g * 16384 + rr * 128 + cc * 8); }
;     const int s = tid & 127, dg = tid >> 7, row = row0 + s;
;     f32x4 pst[8];
; #pragma unroll
;     for (int i = 0; i < 8; ++i) pst[i] = *(const f32x4*)(VST + (size_t)row * 32 + 4 * i);
;     const u32x4 a = *(const u32x4*)(Vg + (size_t)row * 512 + g * 64 + dg * 16), b = *(const u32x4*)(Vg + (size_t)row * 512 + g * 64 + dg * 16 + 8);
;     bf16_t* up = U + (size_t)(row0 + t) * 512 + g * 64 + 4 * q;
;     u32x2 uu[4];
; #pragma unroll
;     for (int db = 0; db < 4; ++db) uu[db] = *(const u32x2*)(up + 16 * db);
;     const float bias = sgb[g * 128 + t];
; #pragma unroll
;     for (int i = 0; i < 4; ++i) { const int c = tid + i * 512, rr = c >> 4, cc = c & 15; *(LAS u32x4*)(Wl + rr * RS + cc * 16) = wreg[i]; }
; __global__ void __launch_bounds__(512, 2) fwd_mega(Args args) {
;     ...
;         if (!dry) { int par = 0; for (int it = bx; it < 1024; it += G, par ^= 1) sgu_item(it >> 7, it & 127, par, wSG, VG, VST, args.in[9], args.in[10], args.in[12], U, lds); __syncthreads(); }
.LBB0_1301:
	s_cmpk_gt_i32 s96, 0x3ff
	s_waitcnt vmcnt(0) lgkmcnt(0)
	s_barrier
	s_cbranch_scc1 .LBB0_1306
	v_mov_b32_e32 v1, 0x20408
	ds_read_b32 v1, v1
	s_waitcnt lgkmcnt(0)
	v_readfirstlane_b32 s98, v1
	s_mov_b32 s99, 0
	v_lshrrev_b32_e32 v1, 4, v196
	v_mul_u32_u24_e32 v43, 0x110, v1
	v_add_u32_e32 v1, 0x200, v196
	v_lshrrev_b32_e32 v1, 4, v1
	v_mul_u32_u24_e32 v44, 0x110, v1
	v_add_u32_e32 v1, 0x600, v196
	v_lshrrev_b32_e32 v1, 4, v1
	s_movk_i32 s2, 0x110
	v_mul_u32_u24_e32 v45, 0x110, v1
	v_mov_b32_e32 v1, 0x220
	v_mad_u32_u24 v48, v131, s2, v1
	v_mov_b32_e32 v1, 0x440
	v_mad_u32_u24 v49, v131, s2, v1
	v_mov_b32_e32 v1, 0x660
	v_mad_u32_u24 v50, v131, s2, v1
	v_mov_b32_e32 v1, 0x880
	v_mad_u32_u24 v51, v131, s2, v1
	v_mov_b32_e32 v1, 0xaa0
	v_mad_u32_u24 v52, v131, s2, v1
	v_mov_b32_e32 v1, 0xcc0
	v_mad_u32_u24 v53, v131, s2, v1
	v_mov_b32_e32 v1, 0xee0
	v_mad_u32_u24 v54, v131, s2, v1
	s_add_u32 s2, s6, 0x7300000
	s_addc_u32 s3, s7, 0
	s_add_u32 s4, s6, 0x3800000
	v_lshlrev_b32_e32 v3, 3, v196
	v_mov_b32_e32 v17, 0
	s_addc_u32 s5, s7, 0
	v_and_b32_e32 v0, 0x1f80, v3
	v_add_u32_e32 v2, 0x1000, v3
	v_add_u32_e32 v3, 0x3000, v3
	v_and_b32_e32 v18, 0xf0, v160
	s_add_u32 s8, s6, 0x6300000
	v_mov_b32_e32 v19, v17
	v_mul_u32_u24_e32 v1, 0x110, v129
	v_and_b32_e32 v2, 0x3f80, v2
	v_and_b32_e32 v4, 0x7f80, v3
	v_and_b32_e32 v42, 0x7f, v196
	v_lshlrev_b32_e32 v6, 2, v161
	s_addc_u32 s9, s7, 0
	v_lshl_add_u64 v[8:9], s[6:7], 0, v[18:19]
	s_mov_b64 s[6:7], 0x3500000
	v_add3_u32 v19, v1, v143, 0
	v_lshlrev_b32_e32 v46, 1, v42
	v_mul_u32_u24_e32 v47, 0x110, v131
	v_lshl_add_u64 v[20:21], v[8:9], 0, s[6:7]
	s_mov_b32 s6, 0
	v_add_u32_e32 v55, 0x8800, v19
	v_lshlrev_b32_e32 v22, 1, v0
	v_mov_b32_e32 v23, v17
	v_lshlrev_b32_e32 v24, 1, v2
	v_mov_b32_e32 v25, v17
	s_movk_i32 s7, 0x4000
	v_lshlrev_b32_e32 v26, 1, v4
	v_mov_b32_e32 v27, v17
	v_lshlrev_b32_e32 v28, 1, v131
	v_mov_b32_e32 v29, v17
	v_lshlrev_b32_e32 v30, 1, v6
	v_mov_b32_e32 v31, v17
	s_mov_b32 s10, 0x3b000000
	s_movk_i32 s11, 0x7fff
	s_mov_b32 s12, s96
.LBB0_1303:
	s_cmp_lg_u32 s98, 0
	s_cbranch_scc0 .Lsgu_orig
	s_and_b32 s100, s96, 7
	s_lshr_b32 s101, s96, 3
	s_lshl_b32 s101, s101, 2
	s_add_i32 s101, s101, s99
	s_lshr_b32 s12, s101, 4
	s_lshl_b32 s12, s12, 7
	s_and_b32 s101, s101, 15
	s_lshl_b32 s100, s100, 4
	s_add_i32 s12, s12, s100
	s_add_i32 s12, s12, s101

; #define LAS __attribute__((address_space(3)))
; DI unsigned pk2(float lo, float hi) { typedef float v2f __attribute__((ext_vector_type(2))); typedef __bf16 v2b __attribute__((ext_vector_type(2))); v2f v = {lo, hi}; v2b b = __builtin_convertvector(v, v2b); return __builtin_bit_cast(unsigned, b); }
; DI float bflo(unsigned w) { return __uint_as_float(w << 16); }
; DI float bfhi(unsigned w) { return __uint_as_float(w & 0xffff0000u); }
; #define MFMA16(a, b, c) __builtin_amdgcn_mfma_f32_16x16x32_bf16((a), (b), (c), 0, 0, 0)
; DI void sgu_item(int g, int bc, int par, const bf16_t* SGW, const bf16_t* Vg, const float* VST, const float* lng, const float* lnb, const float* sgb, bf16_t* U, LAS unsigned char* lds) {
;     ...
;     for (int ks = 0; ks < nks; ++ks) {
;         const bf16x8 bw = *(const LAS bf16x8*)(Wl + (t0 + j) * RS + (32 * ks + 8 * q) * 2);
; #pragma unroll
;         for (int db = 0; db < 4; ++db) { const bf16x8 av = *(const LAS bf16x8*)(Vl + (16 * db + j) * RS + (32 * ks + 8 * q) * 2); acc[db] = MFMA16(av, bw, acc[db]); }
;     }
; #pragma unroll
;     for (int db = 0; db < 4; ++db) {
;         u32x2 wv; wv.x = pk2(bflo(uu[db].x) * (acc[db][0] + bias), bfhi(uu[db].x) * (acc[db][1] + bias)); wv.y = pk2(bflo(uu[db].y) * (acc[db][2] + bias), bfhi(uu[db].y) * (acc[db][3] + bias));
;         *(u32x2*)(up + 16 * db) = wv;
;     }
; __global__ void __launch_bounds__(512, 2) fwd_mega(Args args) {
;     ...
;         if (!dry) { int par = 0; for (int it = bx; it < 1024; it += G, par ^= 1) sgu_item(it >> 7, it & 127, par, wSG, VG, VST, args.in[9], args.in[10], args.in[12], U, lds); __syncthreads(); }
.LBB0_1304:
	ds_read_b128 v[58:61], v56
	ds_read_b128 v[62:65], v57
	ds_read_b128 v[66:69], v56 offset:4352
	s_add_i32 s15, s15, -1
	s_cmp_lg_u32 s15, 0
	v_add_u32_e32 v57, 64, v57
	s_waitcnt lgkmcnt(1)
	v_mfma_f32_16x16x32_bf16 v[12:15], v[58:61], v[62:65], v[12:15]
	ds_read_b128 v[58:61], v56 offset:8704
	s_waitcnt lgkmcnt(1)
	v_mfma_f32_16x16x32_bf16 v[8:11], v[66:69], v[62:65], v[8:11]
	ds_read_b128 v[66:69], v56 offset:13056
	v_add_u32_e32 v56, 64, v56
	s_waitcnt lgkmcnt(1)
	v_mfma_f32_16x16x32_bf16 v[4:7], v[58:61], v[62:65], v[4:7]
	s_waitcnt lgkmcnt(0)
	v_mfma_f32_16x16x32_bf16 v[0:3], v[66:69], v[62:65], v[0:3]
	s_cbranch_scc1 .LBB0_1304
	v_lshlrev_b32_e32 v56, 16, v40
	v_and_b32_e32 v57, 0xffff0000, v40
	v_pk_add_f32 v[12:13], v[16:17], v[12:13] op_sel_hi:[0,1]
	v_lshlrev_b32_e32 v40, 16, v41
	v_and_b32_e32 v41, 0xffff0000, v41
	v_pk_add_f32 v[14:15], v[16:17], v[14:15] op_sel_hi:[0,1]
	v_pk_mul_f32 v[12:13], v[12:13], v[56:57]
	v_pk_mul_f32 v[14:15], v[14:15], v[40:41]
	v_cvt_pk_bf16_f32 v12, v12, v13
	v_cvt_pk_bf16_f32 v13, v14, v15
	flat_store_dwordx2 v[32:33], v[12:13]
	v_lshlrev_b32_e32 v12, 16, v38
	v_and_b32_e32 v13, 0xffff0000, v38
	v_pk_add_f32 v[8:9], v[16:17], v[8:9] op_sel_hi:[0,1]
	v_pk_mul_f32 v[8:9], v[8:9], v[12:13]
	v_lshlrev_b32_e32 v12, 16, v39
	v_and_b32_e32 v13, 0xffff0000, v39
	v_pk_add_f32 v[10:11], v[16:17], v[10:11] op_sel_hi:[0,1]
	v_pk_mul_f32 v[10:11], v[10:11], v[12:13]
	v_cvt_pk_bf16_f32 v8, v8, v9
	v_cvt_pk_bf16_f32 v9, v10, v11
	flat_store_dwordx2 v[32:33], v[8:9] offset:32
	v_lshlrev_b32_e32 v8, 16, v36
	v_and_b32_e32 v9, 0xffff0000, v36
	v_pk_add_f32 v[4:5], v[16:17], v[4:5] op_sel_hi:[0,1]
	v_pk_mul_f32 v[4:5], v[4:5], v[8:9]
	v_lshlrev_b32_e32 v8, 16, v37
	v_and_b32_e32 v9, 0xffff0000, v37
	v_pk_add_f32 v[6:7], v[16:17], v[6:7] op_sel_hi:[0,1]
	v_pk_mul_f32 v[6:7], v[6:7], v[8:9]
	v_cvt_pk_bf16_f32 v4, v4, v5
	v_cvt_pk_bf16_f32 v5, v6, v7
	flat_store_dwordx2 v[32:33], v[4:5] offset:64
	v_lshlrev_b32_e32 v4, 16, v34
	v_and_b32_e32 v5, 0xffff0000, v34
	v_pk_add_f32 v[0:1], v[16:17], v[0:1] op_sel_hi:[0,1]
	v_pk_mul_f32 v[0:1], v[0:1], v[4:5]
	v_lshlrev_b32_e32 v4, 16, v35
	v_and_b32_e32 v5, 0xffff0000, v35
	v_pk_add_f32 v[2:3], v[16:17], v[2:3] op_sel_hi:[0,1]
	v_pk_mul_f32 v[2:3], v[2:3], v[4:5]
	s_add_i32 s12, s12, s86
	s_xor_b32 s6, s6, 1
	v_cvt_pk_bf16_f32 v0, v0, v1
	v_cvt_pk_bf16_f32 v1, v2, v3
	s_add_i32 s99, s99, 1
	s_cmp_gt_i32 s99, 3
	s_cselect_b32 s100, 1, 0
	s_cmpk_gt_i32 s12, 0x3ff
	s_cselect_b32 s101, 1, 0
	s_cmp_lg_u32 s98, 0
	s_cselect_b32 s100, s100, s101
	s_cmp_lg_u32 s100, 0
	flat_store_dwordx2 v[32:33], v[0:1] offset:96
	s_cbranch_scc0 .LBB0_1303

; #define LAS __attribute__((address_space(3)))
; #define MFMA32(a, b, c) __builtin_amdgcn_mfma_f32_32x32x16_bf16((a), (b), (c), 0, 0, 0)
; template <int DQK, int DV, bool CAUSAL, int KT, bool PRIO>
; DI void attn_unit(const bf16_t* Qb, int qpitch, const bf16_t* Kb, int kpitch, const bf16_t* Vtb, int vpitch, bf16_t* Ob, int opitch, int q0, int nt, LAS unsigned char* lds, float kbound, const float* qgain, const int* qpos, float qscale) {
;     ...
;             const int key0 = kt * KT + 64 * hf;
;             if (!CAUSAL || key0 <= qlo + 31) {
;                 if (PRIO) {
;                     constexpr int KSN = DQK / 16, NDB = DV / 32;
;                     f32x16 s0 = negm, s1 = negm;
;                     const LAS unsigned char* kb = lds + buf * KBUF + (64 * hf + r) * KS + h * 16;
;                     const LAS unsigned char* vb = lds + VOFF + buf * VBUF + r * VS + h * 8 + 128 * hf;
;                     bf16x8 kf0[KSN], kf1[KSN], vf[4][NDB];
; #pragma unroll
;                     for (int ks = 0; ks < KSN; ++ks) { kf0[ks] = *(const LAS bf16x8*)(kb + ks * 32); kf1[ks] = *(const LAS bf16x8*)(kb + 32 * KS + ks * 32); }
;                     __builtin_amdgcn_sched_barrier(0); __builtin_amdgcn_s_setprio(1); __builtin_amdgcn_sched_barrier(0);
; #pragma unroll
;                     for (int ks = 0; ks < KSN; ++ks) { s0 = MFMA32(kf0[ks], qf[ks], s0); s1 = MFMA32(kf1[ks], qf[ks], s1); }
;                     __builtin_amdgcn_sched_barrier(0); __builtin_amdgcn_s_setprio(0); __builtin_amdgcn_sched_barrier(0);
; #pragma unroll
;                     for (int q4 = 0; q4 < 4; ++q4)
; #pragma unroll
;                         for (int d = 0; d < NDB; ++d) { const LAS unsigned char* vp = vb + d * 32 * VS + q4 * 32;
;                             const s16x4 lo = *(const LAS s16x4*)vp, hi = *(const LAS s16x4*)(vp + 16); vf[q4][d] = (bf16x8){lo[0], lo[1], lo[2], lo[3], hi[0], hi[1], hi[2], hi[3]}; }
;                     if (CAUSAL && key0 + 63 > qlo) {
; #pragma unroll
;                         for (int i = 0; i < 16; ++i) { const int key = key0 + (i & 3) + 8 * (i >> 2) + 4 * h; if (key > qabs) s0[i] = -1e30f; if (key + 32 > qabs) s1[i] = -1e30f; }
.LBB0_1495:
	ds_read_b128 v[2:5], v194
	ds_read_b128 v[6:9], v194 offset:32
	ds_read_b128 v[10:13], v194 offset:6656
	ds_read_b128 v[140:143], v194 offset:6688
	ds_read_b128 v[144:147], v194 offset:64
	ds_read_b128 v[148:151], v194 offset:96
	ds_read_b128 v[152:155], v194 offset:6720
	ds_read_b128 v[156:159], v194 offset:6752
	ds_read_b128 v[198:201], v194 offset:128
	ds_read_b128 v[202:205], v194 offset:160
	ds_read_b128 v[206:209], v194 offset:6784
	ds_read_b128 v[210:213], v194 offset:6816
	s_setprio 1
	s_setprio 0
	s_waitcnt lgkmcnt(0)
	v_mfma_f32_32x32x16_bf16 v[80:95], v[2:5], v[116:119], v[48:63]
	s_cmp_le_i32 s71, s69
	v_mfma_f32_32x32x16_bf16 v[64:79], v[10:13], v[116:119], v[48:63]
	v_mfma_f32_32x32x16_bf16 v[80:95], v[6:9], v[120:123], v[80:95]
	v_mfma_f32_32x32x16_bf16 v[64:79], v[140:143], v[120:123], v[64:79]
	v_mfma_f32_32x32x16_bf16 v[80:95], v[144:147], v[124:127], v[80:95]
	v_mfma_f32_32x32x16_bf16 v[64:79], v[152:155], v[124:127], v[64:79]
	ds_read_b128 v[152:155], v14
	ds_read_b128 v[140:143], v14 offset:32
	v_mfma_f32_32x32x16_bf16 v[80:95], v[148:151], v[128:131], v[80:95]
	v_mfma_f32_32x32x16_bf16 v[64:79], v[156:159], v[128:131], v[64:79]
	ds_read_b128 v[156:159], v15
	ds_read_b128 v[148:151], v15 offset:32
	ds_read_b128 v[144:147], v14 offset:64
	ds_read_b128 v[10:13], v15 offset:64
	ds_read_b128 v[6:9], v14 offset:96
	ds_read_b128 v[2:5], v15 offset:96
	v_mfma_f32_32x32x16_bf16 v[80:95], v[198:201], v[132:135], v[80:95]
	v_mfma_f32_32x32x16_bf16 v[64:79], v[206:209], v[132:135], v[64:79]
	v_mfma_f32_32x32x16_bf16 v[80:95], v[202:205], v[136:139], v[80:95]
	v_mfma_f32_32x32x16_bf16 v[64:79], v[210:213], v[136:139], v[64:79]
	s_cbranch_scc1 .LBB0_1497
	v_add_u32_e32 v195, s71, v180
	v_subrev_u32_e32 v198, 31, v195
	v_subrev_u32_e32 v197, 63, v195
	v_cmp_le_i32_e32 vcc, v198, v189
	s_nop 6
	v_cndmask_b32_e32 v64, v177, v64, vcc
	v_cmp_lt_i32_e32 vcc, v197, v189
	s_nop 1
	v_cndmask_b32_e32 v81, v177, v81, vcc
	v_cmp_le_i32_e32 vcc, v197, v189
	v_subrev_u32_e32 v197, 30, v195
	s_nop 0
	v_cndmask_b32_e32 v80, v177, v80, vcc
	v_cmp_le_i32_e32 vcc, v197, v189
	v_subrev_u32_e32 v197, 61, v195
	s_nop 0
	v_cndmask_b32_e32 v65, v177, v65, vcc
	v_cmp_le_i32_e32 vcc, v197, v189
	v_subrev_u32_e32 v197, 29, v195
	s_nop 0
	v_cndmask_b32_e32 v82, v177, v82, vcc
	v_cmp_le_i32_e32 vcc, v197, v189
	v_subrev_u32_e32 v197, 60, v195
	s_nop 0
	v_cndmask_b32_e32 v66, v177, v66, vcc
	v_cmp_le_i32_e32 vcc, v197, v189
	v_subrev_u32_e32 v197, 28, v195
	s_nop 0
	v_cndmask_b32_e32 v83, v177, v83, vcc
	v_cmp_le_i32_e32 vcc, v197, v189
	v_subrev_u32_e32 v197, 55, v195
	s_nop 0
	v_cndmask_b32_e32 v67, v177, v67, vcc
	v_cmp_le_i32_e32 vcc, v197, v189
	v_subrev_u32_e32 v197, 23, v195
	s_nop 0
	v_cndmask_b32_e32 v84, v177, v84, vcc
	v_cmp_le_i32_e32 vcc, v197, v189
	v_subrev_u32_e32 v197, 54, v195
	s_nop 0
	v_cndmask_b32_e32 v68, v177, v68, vcc
	v_cmp_le_i32_e32 vcc, v197, v189
	v_subrev_u32_e32 v197, 22, v195
	s_nop 0
	v_cndmask_b32_e32 v85, v177, v85, vcc
	v_cmp_le_i32_e32 vcc, v197, v189
	v_subrev_u32_e32 v197, 53, v195
	s_nop 0
	v_cndmask_b32_e32 v69, v177, v69, vcc
	v_cmp_le_i32_e32 vcc, v197, v189
	v_subrev_u32_e32 v197, 21, v195
	s_nop 0
	v_cndmask_b32_e32 v86, v177, v86, vcc
	v_cmp_le_i32_e32 vcc, v197, v189
	v_subrev_u32_e32 v197, 52, v195
	s_nop 0
	v_cndmask_b32_e32 v70, v177, v70, vcc
	v_cmp_le_i32_e32 vcc, v197, v189
	v_subrev_u32_e32 v197, 20, v195
	s_nop 0
	v_cndmask_b32_e32 v87, v177, v87, vcc
	v_cmp_le_i32_e32 vcc, v197, v189
	v_subrev_u32_e32 v197, 47, v195
	s_nop 0
	v_cndmask_b32_e32 v71, v177, v71, vcc
	v_cmp_le_i32_e32 vcc, v197, v189
	v_add_u32_e32 v197, -15, v195
	s_nop 0
	v_cndmask_b32_e32 v88, v177, v88, vcc
	v_cmp_le_i32_e32 vcc, v197, v189
	v_subrev_u32_e32 v197, 46, v195
	s_nop 0
	v_cndmask_b32_e32 v72, v177, v72, vcc
	v_cmp_le_i32_e32 vcc, v197, v189
	v_add_u32_e32 v197, -14, v195
	s_nop 0
	v_cndmask_b32_e32 v89, v177, v89, vcc
	v_cmp_le_i32_e32 vcc, v197, v189
	v_subrev_u32_e32 v197, 45, v195
	s_nop 0
	v_cndmask_b32_e32 v73, v177, v73, vcc
	v_cmp_le_i32_e32 vcc, v197, v189
	v_add_u32_e32 v197, -13, v195
	s_nop 0
	v_cndmask_b32_e32 v90, v177, v90, vcc
	v_cmp_le_i32_e32 vcc, v197, v189
	v_subrev_u32_e32 v197, 44, v195
	s_nop 0
	v_cndmask_b32_e32 v74, v177, v74, vcc
	v_cmp_le_i32_e32 vcc, v197, v189
	v_add_u32_e32 v197, -12, v195
	s_nop 0
	v_cndmask_b32_e32 v91, v177, v91, vcc
	v_cmp_le_i32_e32 vcc, v197, v189
	v_subrev_u32_e32 v197, 39, v195
	s_nop 0
	v_cndmask_b32_e32 v75, v177, v75, vcc
	v_cmp_le_i32_e32 vcc, v197, v189
	v_add_u32_e32 v197, -7, v195
	s_nop 0
	v_cndmask_b32_e32 v92, v177, v92, vcc
	v_cmp_le_i32_e32 vcc, v197, v189
	v_subrev_u32_e32 v197, 38, v195
	s_nop 0
	v_cndmask_b32_e32 v76, v177, v76, vcc
	v_cmp_le_i32_e32 vcc, v197, v189
	v_add_u32_e32 v197, -6, v195
	s_nop 0
	v_cndmask_b32_e32 v93, v177, v93, vcc
	v_cmp_le_i32_e32 vcc, v197, v189
	v_subrev_u32_e32 v197, 37, v195
	s_nop 0
	v_cndmask_b32_e32 v77, v177, v77, vcc
	v_cmp_le_i32_e32 vcc, v197, v189
	v_add_u32_e32 v197, -5, v195
	s_nop 0
	v_cndmask_b32_e32 v94, v177, v94, vcc
	v_cmp_le_i32_e32 vcc, v197, v189
	v_subrev_u32_e32 v197, 36, v195
	v_add_u32_e32 v195, -4, v195
	v_cndmask_b32_e32 v78, v177, v78, vcc
	v_cmp_le_i32_e32 vcc, v197, v189
	s_nop 1
	v_cndmask_b32_e32 v95, v177, v95, vcc
	v_cmp_le_i32_e32 vcc, v195, v189
	s_nop 1
	v_cndmask_b32_e32 v79, v177, v79, vcc

; #define LAS __attribute__((address_space(3)))
; #define MFMA32(a, b, c) __builtin_amdgcn_mfma_f32_32x32x16_bf16((a), (b), (c), 0, 0, 0)
; template <int DQK, int DV, bool CAUSAL, int KT, bool PRIO>
; DI void attn_unit(const bf16_t* Qb, int qpitch, const bf16_t* Kb, int kpitch, const bf16_t* Vtb, int vpitch, bf16_t* Ob, int opitch, int q0, int nt, LAS unsigned char* lds, float kbound, const float* qgain, const int* qpos, float qscale) {
;     ...
;             const int key0 = kt * KT + 64 * hf;
;             if (!CAUSAL || key0 <= qlo + 31) {
;                 if (PRIO) {
;                     constexpr int KSN = DQK / 16, NDB = DV / 32;
;                     f32x16 s0 = negm, s1 = negm;
;                     const LAS unsigned char* kb = lds + buf * KBUF + (64 * hf + r) * KS + h * 16;
;                     const LAS unsigned char* vb = lds + VOFF + buf * VBUF + r * VS + h * 8 + 128 * hf;
;                     bf16x8 kf0[KSN], kf1[KSN], vf[4][NDB];
; #pragma unroll
;                     for (int ks = 0; ks < KSN; ++ks) { kf0[ks] = *(const LAS bf16x8*)(kb + ks * 32); kf1[ks] = *(const LAS bf16x8*)(kb + 32 * KS + ks * 32); }
;                     __builtin_amdgcn_sched_barrier(0); __builtin_amdgcn_s_setprio(1); __builtin_amdgcn_sched_barrier(0);
; #pragma unroll
;                     for (int ks = 0; ks < KSN; ++ks) { s0 = MFMA32(kf0[ks], qf[ks], s0); s1 = MFMA32(kf1[ks], qf[ks], s1); }
;                     __builtin_amdgcn_sched_barrier(0); __builtin_amdgcn_s_setprio(0); __builtin_amdgcn_sched_barrier(0);
; #pragma unroll
;                     for (int q4 = 0; q4 < 4; ++q4)
; #pragma unroll
;                         for (int d = 0; d < NDB; ++d) { const LAS unsigned char* vp = vb + d * 32 * VS + q4 * 32;
;                             const s16x4 lo = *(const LAS s16x4*)vp, hi = *(const LAS s16x4*)(vp + 16); vf[q4][d] = (bf16x8){lo[0], lo[1], lo[2], lo[3], hi[0], hi[1], hi[2], hi[3]}; }
;                     if (CAUSAL && key0 + 63 > qlo) {
; #pragma unroll
;                         for (int i = 0; i < 16; ++i) { const int key = key0 + (i & 3) + 8 * (i >> 2) + 4 * h; if (key > qabs) s0[i] = -1e30f; if (key + 32 > qabs) s1[i] = -1e30f; }
.LBB0_1505:
	ds_read_b128 v[2:5], v194 offset:13312
	ds_read_b128 v[6:9], v194 offset:13344
	ds_read_b128 v[10:13], v194 offset:19968
	ds_read_b128 v[140:143], v194 offset:20000
	ds_read_b128 v[144:147], v194 offset:13376
	ds_read_b128 v[148:151], v194 offset:13408
	ds_read_b128 v[152:155], v194 offset:20032
	ds_read_b128 v[156:159], v194 offset:20064
	ds_read_b128 v[198:201], v194 offset:13440
	ds_read_b128 v[202:205], v194 offset:13472
	ds_read_b128 v[206:209], v194 offset:20096
	ds_read_b128 v[210:213], v194 offset:20128
	s_setprio 1
	s_setprio 0
	s_waitcnt lgkmcnt(0)
	v_mfma_f32_32x32x16_bf16 v[80:95], v[2:5], v[116:119], v[48:63]
	s_add_i32 s12, s71, 64
	s_cmp_le_i32 s12, s69
	v_mfma_f32_32x32x16_bf16 v[64:79], v[10:13], v[116:119], v[48:63]
	v_mfma_f32_32x32x16_bf16 v[80:95], v[6:9], v[120:123], v[80:95]
	v_mfma_f32_32x32x16_bf16 v[64:79], v[140:143], v[120:123], v[64:79]
	v_mfma_f32_32x32x16_bf16 v[80:95], v[144:147], v[124:127], v[80:95]
	v_mfma_f32_32x32x16_bf16 v[64:79], v[152:155], v[124:127], v[64:79]
	v_mfma_f32_32x32x16_bf16 v[80:95], v[148:151], v[128:131], v[80:95]
	v_mfma_f32_32x32x16_bf16 v[64:79], v[156:159], v[128:131], v[64:79]
	ds_read_b128 v[156:159], v14 offset:128
	ds_read_b128 v[140:143], v14 offset:160
	ds_read_b128 v[152:155], v15 offset:128
	ds_read_b128 v[148:151], v15 offset:160
	ds_read_b128 v[144:147], v14 offset:192
	ds_read_b128 v[10:13], v15 offset:192
	ds_read_b128 v[6:9], v14 offset:224
	ds_read_b128 v[2:5], v15 offset:224
	v_mfma_f32_32x32x16_bf16 v[80:95], v[198:201], v[132:135], v[80:95]
	v_mfma_f32_32x32x16_bf16 v[64:79], v[206:209], v[132:135], v[64:79]
	v_mfma_f32_32x32x16_bf16 v[80:95], v[202:205], v[136:139], v[80:95]
	v_mfma_f32_32x32x16_bf16 v[64:79], v[210:213], v[136:139], v[64:79]
	s_cbranch_scc1 .LBB0_1507
	v_add_u32_e32 v14, s71, v180
	v_add_u32_e32 v194, 33, v14
	v_add_u32_e32 v15, 1, v14
	v_cmp_le_i32_e32 vcc, v194, v189
	s_nop 6
	v_cndmask_b32_e32 v64, v177, v64, vcc
	v_cmp_lt_i32_e32 vcc, v15, v189
	s_nop 1
	v_cndmask_b32_e32 v81, v177, v81, vcc
	v_cmp_le_i32_e32 vcc, v15, v189
	v_add_u32_e32 v15, 34, v14
	s_nop 0
	v_cndmask_b32_e32 v80, v177, v80, vcc
	v_cmp_le_i32_e32 vcc, v15, v189
	v_add_u32_e32 v15, 3, v14
	s_nop 0
	v_cndmask_b32_e32 v65, v177, v65, vcc
	v_cmp_le_i32_e32 vcc, v15, v189
	v_add_u32_e32 v15, 35, v14
	s_nop 0
	v_cndmask_b32_e32 v82, v177, v82, vcc
	v_cmp_le_i32_e32 vcc, v15, v189
	v_add_u32_e32 v15, 4, v14
	s_nop 0
	v_cndmask_b32_e32 v66, v177, v66, vcc
	v_cmp_le_i32_e32 vcc, v15, v189
	v_add_u32_e32 v15, 36, v14
	s_nop 0
	v_cndmask_b32_e32 v83, v177, v83, vcc
	v_cmp_le_i32_e32 vcc, v15, v189
	v_add_u32_e32 v15, 9, v14
	s_nop 0
	v_cndmask_b32_e32 v67, v177, v67, vcc
	v_cmp_le_i32_e32 vcc, v15, v189
	v_add_u32_e32 v15, 41, v14
	s_nop 0
	v_cndmask_b32_e32 v84, v177, v84, vcc
	v_cmp_le_i32_e32 vcc, v15, v189
	v_add_u32_e32 v15, 10, v14
	s_nop 0
	v_cndmask_b32_e32 v68, v177, v68, vcc
	v_cmp_le_i32_e32 vcc, v15, v189
	v_add_u32_e32 v15, 42, v14
	s_nop 0
	v_cndmask_b32_e32 v85, v177, v85, vcc
	v_cmp_le_i32_e32 vcc, v15, v189
	v_add_u32_e32 v15, 11, v14
	s_nop 0
	v_cndmask_b32_e32 v69, v177, v69, vcc
	v_cmp_le_i32_e32 vcc, v15, v189
	v_add_u32_e32 v15, 43, v14
	s_nop 0
	v_cndmask_b32_e32 v86, v177, v86, vcc
	v_cmp_le_i32_e32 vcc, v15, v189
	v_add_u32_e32 v15, 12, v14
	s_nop 0
	v_cndmask_b32_e32 v70, v177, v70, vcc
	v_cmp_le_i32_e32 vcc, v15, v189
	v_add_u32_e32 v15, 44, v14
	s_nop 0
	v_cndmask_b32_e32 v87, v177, v87, vcc
	v_cmp_le_i32_e32 vcc, v15, v189
	v_add_u32_e32 v15, 17, v14
	s_nop 0
	v_cndmask_b32_e32 v71, v177, v71, vcc
	v_cmp_le_i32_e32 vcc, v15, v189
	v_add_u32_e32 v15, 49, v14
	s_nop 0
	v_cndmask_b32_e32 v88, v177, v88, vcc
	v_cmp_le_i32_e32 vcc, v15, v189
	v_add_u32_e32 v15, 18, v14
	s_nop 0
	v_cndmask_b32_e32 v72, v177, v72, vcc
	v_cmp_le_i32_e32 vcc, v15, v189
	v_add_u32_e32 v15, 50, v14
	s_nop 0
	v_cndmask_b32_e32 v89, v177, v89, vcc
	v_cmp_le_i32_e32 vcc, v15, v189
	v_add_u32_e32 v15, 19, v14
	s_nop 0
	v_cndmask_b32_e32 v73, v177, v73, vcc
	v_cmp_le_i32_e32 vcc, v15, v189
	v_add_u32_e32 v15, 51, v14
	s_nop 0
	v_cndmask_b32_e32 v90, v177, v90, vcc
	v_cmp_le_i32_e32 vcc, v15, v189
	v_add_u32_e32 v15, 20, v14
	s_nop 0
	v_cndmask_b32_e32 v74, v177, v74, vcc
	v_cmp_le_i32_e32 vcc, v15, v189
	v_add_u32_e32 v15, 52, v14
	s_nop 0
	v_cndmask_b32_e32 v91, v177, v91, vcc
	v_cmp_le_i32_e32 vcc, v15, v189
	v_add_u32_e32 v15, 25, v14
	s_nop 0
	v_cndmask_b32_e32 v75, v177, v75, vcc
	v_cmp_le_i32_e32 vcc, v15, v189
	v_add_u32_e32 v15, 57, v14
	s_nop 0
	v_cndmask_b32_e32 v92, v177, v92, vcc
	v_cmp_le_i32_e32 vcc, v15, v189
	v_add_u32_e32 v15, 26, v14
	s_nop 0
	v_cndmask_b32_e32 v76, v177, v76, vcc
	v_cmp_le_i32_e32 vcc, v15, v189
	v_add_u32_e32 v15, 58, v14
	s_nop 0
	v_cndmask_b32_e32 v93, v177, v93, vcc
	v_cmp_le_i32_e32 vcc, v15, v189
	v_add_u32_e32 v15, 27, v14
	s_nop 0
	v_cndmask_b32_e32 v77, v177, v77, vcc
	v_cmp_le_i32_e32 vcc, v15, v189
	v_add_u32_e32 v15, 59, v14
	s_nop 0
	v_cndmask_b32_e32 v94, v177, v94, vcc
	v_cmp_le_i32_e32 vcc, v15, v189
	v_add_u32_e32 v15, 28, v14
	v_add_u32_e32 v14, 60, v14
	v_cndmask_b32_e32 v78, v177, v78, vcc
	v_cmp_le_i32_e32 vcc, v15, v189
	s_nop 1
	v_cndmask_b32_e32 v95, v177, v95, vcc
	v_cmp_le_i32_e32 vcc, v14, v189
	s_nop 1
	v_cndmask_b32_e32 v79, v177, v79, vcc

; __global__ void __launch_bounds__(512, 2) fwd_mega(Args args) {
	.amdhsa_kernel _Z8fwd_mega4Args
		.amdhsa_group_segment_fixed_size 0
		.amdhsa_private_segment_fixed_size 0
		.amdhsa_kernarg_size 520
		.amdhsa_user_sgpr_count 2
		.amdhsa_user_sgpr_dispatch_ptr 0
		.amdhsa_user_sgpr_queue_ptr 0
		.amdhsa_user_sgpr_kernarg_segment_ptr 1
		.amdhsa_user_sgpr_dispatch_id 0
		.amdhsa_user_sgpr_kernarg_preload_length 0
		.amdhsa_user_sgpr_kernarg_preload_offset 0
		.amdhsa_user_sgpr_private_segment_size 0
		.amdhsa_uses_dynamic_stack 0
		.amdhsa_enable_private_segment 0
		.amdhsa_system_sgpr_workgroup_id_x 1
		.amdhsa_system_sgpr_workgroup_id_y 0
		.amdhsa_system_sgpr_workgroup_id_z 0
		.amdhsa_system_sgpr_workgroup_info 0
		.amdhsa_system_vgpr_workitem_id 2
		.amdhsa_next_free_vgpr 256
		.amdhsa_next_free_sgpr 102
		.amdhsa_accum_offset 256
		.amdhsa_reserve_vcc 1
		.amdhsa_float_round_mode_32 0
		.amdhsa_float_round_mode_16_64 0
		.amdhsa_float_denorm_mode_32 3
		.amdhsa_float_denorm_mode_16_64 3
		.amdhsa_dx10_clamp 1
		.amdhsa_ieee_mode 1
		.amdhsa_fp16_overflow 0
		.amdhsa_tg_split 0
		.amdhsa_exception_fp_ieee_invalid_op 0
		.amdhsa_exception_fp_denorm_src 0
		.amdhsa_exception_fp_ieee_div_zero 0
		.amdhsa_exception_fp_ieee_overflow 0
		.amdhsa_exception_fp_ieee_underflow 0
		.amdhsa_exception_fp_ieee_inexact 0
		.amdhsa_exception_int_div_zero 0
	.end_amdhsa_kernel

; __global__ void __launch_bounds__(512, 2) fwd_mega(Args args) {
amdhsa.kernels:
  - .agpr_count:     0
    .args:
      - .offset:         0
        .size:           264
        .value_kind:     by_value
      - .offset:         264
        .size:           4
        .value_kind:     hidden_block_count_x
      - .offset:         268
        .size:           4
        .value_kind:     hidden_block_count_y
      - .offset:         272
        .size:           4
        .value_kind:     hidden_block_count_z
      - .offset:         276
        .size:           2
        .value_kind:     hidden_group_size_x
      - .offset:         278
        .size:           2
        .value_kind:     hidden_group_size_y
      - .offset:         280
        .size:           2
        .value_kind:     hidden_group_size_z
      - .offset:         282
        .size:           2
        .value_kind:     hidden_remainder_x
      - .offset:         284
        .size:           2
        .value_kind:     hidden_remainder_y
      - .offset:         286
        .size:           2
        .value_kind:     hidden_remainder_z
      - .offset:         304
        .size:           8
        .value_kind:     hidden_global_offset_x
      - .offset:         312
        .size:           8
        .value_kind:     hidden_global_offset_y
      - .offset:         320
        .size:           8
        .value_kind:     hidden_global_offset_z
      - .offset:         328
        .size:           2
        .value_kind:     hidden_grid_dims
      - .offset:         352
        .size:           8
        .value_kind:     hidden_multigrid_sync_arg
      - .offset:         384
        .size:           4
        .value_kind:     hidden_dynamic_lds_size
    .group_segment_fixed_size: 0
    .kernarg_segment_align: 8
    .kernarg_segment_size: 520
    .language:       OpenCL C
    .language_version:
      - 2
      - 0
    .max_flat_workgroup_size: 512
    .name:           _Z8fwd_mega4Args
    .private_segment_fixed_size: 0
    .sgpr_count:     108
    .sgpr_spill_count: 88
    .symbol:         _Z8fwd_mega4Args.kd
    .uniform_work_group_size: 1
    .uses_dynamic_stack: false
    .vgpr_count:     256
    .vgpr_spill_count: 0
    .wavefront_size: 64
